# P8 epilogue (out += acc) stores marked sc0 sc1 (write-through), as already done for the P1 epilogue
# baseline (speedup 1.0000x reference)
;     __device__ __forceinline__ void operator()(const f32x4 (&acc)[2][2][4][2], const Unit& u, int wr, int wc, int fr, int fq) const {
;     ...
;         for (int ai = 0; ai < 2; ++ai)
; #pragma unroll
;             for (int m = 0; m < 4; ++m) { const size_t row = (size_t)(row0 + ai * HALF + m * 16);
; #pragma unroll
;                 for (int bj = 0; bj < 2; ++bj) { const int col = u.pn * BM + bj * HALF + wc * 32 + 8 * fq; float* op = out + row * 2048 + col;
;                     const f32x4 a0 = *(const f32x4*)op + acc[ai][bj][m][0], a1 = *(const f32x4*)(op + 4) + acc[ai][bj][m][1];
;                     *(f32x4*)op = a0; *(f32x4*)(op + 4) = a1; } }
.LBB0_745:
	v_lshl_add_u32 v146, s53, 8, v150
	v_lshl_or_b32 v144, s54, 8, v152
	v_ashrrev_i32_e32 v147, 31, v146
	v_lshlrev_b64 v[148:149], 13, v[146:147]
	v_ashrrev_i32_e32 v145, 31, v144
	v_lshl_add_u64 v[156:157], s[26:27], 0, v[148:149]
	v_lshlrev_b64 v[148:149], 2, v[144:145]
	v_lshl_add_u64 v[144:145], v[156:157], 0, v[148:149]
	global_load_dwordx4 v[156:159], v[144:145], off offset:16
	global_load_dwordx4 v[160:163], v[144:145], off
	s_mov_b64 s[22:23], -1
	s_waitcnt vmcnt(0)
	v_pk_add_f32 v[122:123], v[122:123], v[158:159]
	v_pk_add_f32 v[126:127], v[126:127], v[162:163]
	v_pk_add_f32 v[124:125], v[124:125], v[160:161]
	v_pk_add_f32 v[120:121], v[120:121], v[156:157]
	global_store_dwordx4 v[144:145], v[124:127], off sc0 sc1
	global_store_dwordx4 v[144:145], v[120:123], off offset:16 sc0 sc1
	global_load_dwordx4 v[120:123], v[144:145], off offset:528
	s_nop 0
	global_load_dwordx4 v[124:127], v[144:145], off offset:512
	s_waitcnt vmcnt(1)
	v_pk_add_f32 v[112:113], v[112:113], v[120:121]
	s_waitcnt vmcnt(0)
	v_pk_add_f32 v[118:119], v[118:119], v[126:127]
	v_pk_add_f32 v[116:117], v[116:117], v[124:125]
	v_pk_add_f32 v[114:115], v[114:115], v[122:123]
	global_store_dwordx4 v[144:145], v[116:119], off offset:512 sc0 sc1
	global_store_dwordx4 v[144:145], v[112:115], off offset:528 sc0 sc1
	s_nop 1
	v_or_b32_e32 v112, 16, v146
	v_ashrrev_i32_e32 v113, 31, v112
	v_lshlrev_b64 v[112:113], 13, v[112:113]
	v_lshl_add_u64 v[112:113], s[26:27], 0, v[112:113]
	v_lshl_add_u64 v[120:121], v[112:113], 0, v[148:149]
	global_load_dwordx4 v[112:115], v[120:121], off offset:16
	global_load_dwordx4 v[116:119], v[120:121], off
	s_waitcnt vmcnt(1)
	v_pk_add_f32 v[106:107], v[106:107], v[114:115]
	s_waitcnt vmcnt(0)
	v_pk_add_f32 v[110:111], v[110:111], v[118:119]
	v_pk_add_f32 v[108:109], v[108:109], v[116:117]
	v_pk_add_f32 v[104:105], v[104:105], v[112:113]
	global_store_dwordx4 v[120:121], v[108:111], off sc0 sc1
	global_store_dwordx4 v[120:121], v[104:107], off offset:16 sc0 sc1
	global_load_dwordx4 v[104:107], v[120:121], off offset:528
	s_nop 0
	global_load_dwordx4 v[108:111], v[120:121], off offset:512
	s_waitcnt vmcnt(1)
	v_pk_add_f32 v[96:97], v[96:97], v[104:105]
	s_waitcnt vmcnt(0)
	v_pk_add_f32 v[102:103], v[102:103], v[110:111]
	v_pk_add_f32 v[100:101], v[100:101], v[108:109]
	v_pk_add_f32 v[98:99], v[98:99], v[106:107]
	global_store_dwordx4 v[120:121], v[100:103], off offset:512 sc0 sc1
	global_store_dwordx4 v[120:121], v[96:99], off offset:528 sc0 sc1
	s_nop 1
	v_or_b32_e32 v96, 32, v146
	v_ashrrev_i32_e32 v97, 31, v96
	v_lshlrev_b64 v[96:97], 13, v[96:97]
	v_lshl_add_u64 v[96:97], s[26:27], 0, v[96:97]
	v_lshl_add_u64 v[104:105], v[96:97], 0, v[148:149]
	global_load_dwordx4 v[96:99], v[104:105], off offset:16
	global_load_dwordx4 v[100:103], v[104:105], off
	s_waitcnt vmcnt(1)
	v_pk_add_f32 v[90:91], v[90:91], v[98:99]
	s_waitcnt vmcnt(0)
	v_pk_add_f32 v[94:95], v[94:95], v[102:103]
	v_pk_add_f32 v[92:93], v[92:93], v[100:101]
	v_pk_add_f32 v[88:89], v[88:89], v[96:97]
	global_store_dwordx4 v[104:105], v[92:95], off sc0 sc1
	global_store_dwordx4 v[104:105], v[88:91], off offset:16 sc0 sc1
	global_load_dwordx4 v[88:91], v[104:105], off offset:528
	s_nop 0
	global_load_dwordx4 v[92:95], v[104:105], off offset:512
	s_waitcnt vmcnt(1)
	v_pk_add_f32 v[80:81], v[80:81], v[88:89]
	s_waitcnt vmcnt(0)
	v_pk_add_f32 v[86:87], v[86:87], v[94:95]
	v_pk_add_f32 v[84:85], v[84:85], v[92:93]
	v_pk_add_f32 v[82:83], v[82:83], v[90:91]
	global_store_dwordx4 v[104:105], v[84:87], off offset:512 sc0 sc1
	global_store_dwordx4 v[104:105], v[80:83], off offset:528 sc0 sc1
	s_nop 1
	v_or_b32_e32 v80, 48, v146
	v_ashrrev_i32_e32 v81, 31, v80
	v_lshlrev_b64 v[80:81], 13, v[80:81]
	v_lshl_add_u64 v[80:81], s[26:27], 0, v[80:81]
	v_lshl_add_u64 v[88:89], v[80:81], 0, v[148:149]
	global_load_dwordx4 v[80:83], v[88:89], off offset:16
	global_load_dwordx4 v[84:87], v[88:89], off
	s_waitcnt vmcnt(1)
	v_pk_add_f32 v[74:75], v[74:75], v[82:83]
	s_waitcnt vmcnt(0)
	v_pk_add_f32 v[78:79], v[78:79], v[86:87]
	v_pk_add_f32 v[76:77], v[76:77], v[84:85]
	v_pk_add_f32 v[72:73], v[72:73], v[80:81]
	global_store_dwordx4 v[88:89], v[76:79], off sc0 sc1
	global_store_dwordx4 v[88:89], v[72:75], off offset:16 sc0 sc1
	global_load_dwordx4 v[72:75], v[88:89], off offset:528
	s_nop 0
	global_load_dwordx4 v[76:79], v[88:89], off offset:512
	s_waitcnt vmcnt(1)
	v_pk_add_f32 v[66:67], v[66:67], v[74:75]
	s_waitcnt vmcnt(0)
;     __device__ __forceinline__ void operator()(const f32x4 (&acc)[2][2][4][2], const Unit& u, int wr, int wc, int fr, int fq) const {
;     ...
;         for (int ai = 0; ai < 2; ++ai)
; #pragma unroll
;             for (int m = 0; m < 4; ++m) { const size_t row = (size_t)(row0 + ai * HALF + m * 16);
; #pragma unroll
;                 for (int bj = 0; bj < 2; ++bj) { const int col = u.pn * BM + bj * HALF + wc * 32 + 8 * fq; float* op = out + row * 2048 + col;
;                     const f32x4 a0 = *(const f32x4*)op + acc[ai][bj][m][0], a1 = *(const f32x4*)(op + 4) + acc[ai][bj][m][1];
;                     *(f32x4*)op = a0; *(f32x4*)(op + 4) = a1; } }
	v_pk_add_f32 v[70:71], v[70:71], v[78:79]
	v_pk_add_f32 v[68:69], v[68:69], v[76:77]
	v_add_co_u32_e32 v74, vcc, s47, v144
	v_pk_add_f32 v[64:65], v[64:65], v[72:73]
	global_store_dwordx4 v[88:89], v[68:71], off offset:512 sc0 sc1
	global_store_dwordx4 v[88:89], v[64:67], off offset:528 sc0 sc1
	v_addc_co_u32_e32 v75, vcc, 0, v145, vcc
	v_lshl_add_u64 v[72:73], v[144:145], 0, s[14:15]
	global_load_dwordx4 v[64:67], v[74:75], off
	global_load_dwordx4 v[68:71], v[72:73], off offset:16
	s_waitcnt vmcnt(1)
	v_pk_add_f32 v[62:63], v[62:63], v[66:67]
	v_pk_add_f32 v[60:61], v[60:61], v[64:65]
	s_waitcnt vmcnt(0)
	v_pk_add_f32 v[58:59], v[58:59], v[70:71]
	v_pk_add_f32 v[56:57], v[56:57], v[68:69]
	global_store_dwordx4 v[74:75], v[60:63], off sc0 sc1
	global_store_dwordx4 v[72:73], v[56:59], off offset:16 sc0 sc1
	global_load_dwordx4 v[56:59], v[72:73], off offset:528
	s_nop 0
	global_load_dwordx4 v[60:63], v[72:73], off offset:512
	s_waitcnt vmcnt(1)
	v_pk_add_f32 v[50:51], v[50:51], v[58:59]
	s_waitcnt vmcnt(0)
	v_pk_add_f32 v[54:55], v[54:55], v[62:63]
	v_pk_add_f32 v[52:53], v[52:53], v[60:61]
	v_add_co_u32_e32 v58, vcc, s48, v144
	v_pk_add_f32 v[48:49], v[48:49], v[56:57]
	global_store_dwordx4 v[72:73], v[52:55], off offset:512 sc0 sc1
	global_store_dwordx4 v[72:73], v[48:51], off offset:528 sc0 sc1
	v_addc_co_u32_e32 v59, vcc, 0, v145, vcc
	v_lshl_add_u64 v[56:57], v[144:145], 0, s[16:17]
	global_load_dwordx4 v[48:51], v[58:59], off
	global_load_dwordx4 v[52:55], v[56:57], off offset:16
	s_waitcnt vmcnt(1)
	v_pk_add_f32 v[46:47], v[46:47], v[50:51]
	v_pk_add_f32 v[44:45], v[44:45], v[48:49]
	s_waitcnt vmcnt(0)
	v_pk_add_f32 v[42:43], v[42:43], v[54:55]
	v_pk_add_f32 v[40:41], v[40:41], v[52:53]
	global_store_dwordx4 v[58:59], v[44:47], off sc0 sc1
	global_store_dwordx4 v[56:57], v[40:43], off offset:16 sc0 sc1
	global_load_dwordx4 v[40:43], v[56:57], off offset:528
	s_nop 0
	global_load_dwordx4 v[44:47], v[56:57], off offset:512
	s_waitcnt vmcnt(1)
	v_pk_add_f32 v[34:35], v[34:35], v[42:43]
	s_waitcnt vmcnt(0)
	v_pk_add_f32 v[38:39], v[38:39], v[46:47]
	v_pk_add_f32 v[36:37], v[36:37], v[44:45]
	v_add_co_u32_e32 v42, vcc, s49, v144
	v_pk_add_f32 v[32:33], v[32:33], v[40:41]
	global_store_dwordx4 v[56:57], v[36:39], off offset:512 sc0 sc1
	global_store_dwordx4 v[56:57], v[32:35], off offset:528 sc0 sc1
	v_addc_co_u32_e32 v43, vcc, 0, v145, vcc
	v_lshl_add_u64 v[40:41], v[144:145], 0, s[18:19]
	global_load_dwordx4 v[32:35], v[42:43], off
	global_load_dwordx4 v[36:39], v[40:41], off offset:16
	s_waitcnt vmcnt(1)
	v_pk_add_f32 v[30:31], v[30:31], v[34:35]
	v_pk_add_f32 v[28:29], v[28:29], v[32:33]
	s_waitcnt vmcnt(0)
	v_pk_add_f32 v[26:27], v[26:27], v[38:39]
	v_pk_add_f32 v[24:25], v[24:25], v[36:37]
	global_store_dwordx4 v[42:43], v[28:31], off sc0 sc1
	global_store_dwordx4 v[40:41], v[24:27], off offset:16 sc0 sc1
	global_load_dwordx4 v[24:27], v[40:41], off offset:528
	s_nop 0
	global_load_dwordx4 v[28:31], v[40:41], off offset:512
	s_waitcnt vmcnt(1)
	v_pk_add_f32 v[18:19], v[18:19], v[26:27]
	s_waitcnt vmcnt(0)
	v_pk_add_f32 v[22:23], v[22:23], v[30:31]
	v_pk_add_f32 v[20:21], v[20:21], v[28:29]
	v_add_co_u32_e32 v26, vcc, s50, v144
	v_pk_add_f32 v[16:17], v[16:17], v[24:25]
	global_store_dwordx4 v[40:41], v[20:23], off offset:512 sc0 sc1
	global_store_dwordx4 v[40:41], v[16:19], off offset:528 sc0 sc1
	v_addc_co_u32_e32 v27, vcc, 0, v145, vcc
	s_nop 0
	v_lshl_add_u64 v[16:17], v[144:145], 0, s[6:7]
	global_load_dwordx4 v[18:21], v[26:27], off
	global_load_dwordx4 v[22:25], v[16:17], off offset:16
	s_and_b64 vcc, exec, s[0:1]
	s_waitcnt vmcnt(1)
	v_pk_add_f32 v[14:15], v[14:15], v[20:21]
	v_pk_add_f32 v[12:13], v[12:13], v[18:19]
	s_waitcnt vmcnt(0)
	v_pk_add_f32 v[10:11], v[10:11], v[24:25]
	v_pk_add_f32 v[8:9], v[8:9], v[22:23]
	global_store_dwordx4 v[26:27], v[12:15], off sc0 sc1
	global_store_dwordx4 v[16:17], v[8:11], off offset:16 sc0 sc1
	global_load_dwordx4 v[8:11], v[16:17], off offset:528
	s_nop 0
	global_load_dwordx4 v[12:15], v[16:17], off offset:512
	s_waitcnt vmcnt(1)
	v_pk_add_f32 v[2:3], v[2:3], v[10:11]
	s_waitcnt vmcnt(0)
	v_pk_add_f32 v[6:7], v[6:7], v[14:15]
	v_pk_add_f32 v[4:5], v[4:5], v[12:13]
	v_pk_add_f32 v[0:1], v[0:1], v[8:9]
	global_store_dwordx4 v[16:17], v[4:7], off offset:512 sc0 sc1
	global_store_dwordx4 v[16:17], v[0:3], off offset:528 sc0 sc1
	s_cbranch_vccnz .LBB0_730
	s_andn2_b64 vcc, exec, s[8:9]
	s_cbranch_vccnz .LBB0_729
	s_barrier
	s_branch .LBB0_729
